# final LayerNorm phase: loop-invariant gamma/beta hoisted out of row loop, stats load ahead of prefetch, single counted wait, true 1-deep row pipelining
# baseline (speedup 1.0000x reference)
.LBB0_985:
	s_or_b64 exec, exec, s[0:1]
	v_mov_b32_e32 v36, v216
	v_readlane_b32 s0, v254, 45
	s_barrier
	v_readlane_b32 s6, v254, 51
	v_ashrrev_i32_e32 v0, 6, v36
	v_readlane_b32 s7, v254, 52
	v_readlane_b32 s2, v254, 47
	v_readlane_b32 s3, v254, 48
	v_mov_b32_e32 v1, s6
	v_mov_b32_e32 v2, s7
	v_add_u32_e32 v64, s55, v0
	v_readlane_b32 s1, v254, 46
	v_cmp_gt_i32_e32 vcc, s45, v64
	v_readfirstlane_b32 s2, v1
	v_readfirstlane_b32 s3, v2
	v_readlane_b32 s4, v254, 49
	v_readlane_b32 s5, v254, 50
	s_and_saveexec_b64 s[0:1], vcc
	v_readlane_b32 s14, v254, 58
	v_readlane_b32 s15, v254, 59
	s_mov_b32 s16, 0x3a800000
	s_cbranch_execz .LBB0_988
	v_lshlrev_b32_e32 v0, 2, v36
	v_and_b32_e32 v33, 0xfc, v0
	v_readlane_b32 s4, v254, 3
	v_readlane_b32 s6, v254, 5
	v_lshlrev_b32_e32 v178, 2, v33
	v_readlane_b32 s5, v254, 4
	v_readlane_b32 s7, v254, 6
	s_nop 3
	global_load_dwordx4 v[0:3], v178, s[4:5]
	global_load_dwordx4 v[4:7], v178, s[4:5] offset:1024
	global_load_dwordx4 v[8:11], v178, s[6:7]
	global_load_dwordx4 v[12:15], v178, s[6:7] offset:1024
	global_load_dwordx4 v[16:19], v178, s[4:5] offset:2048
	global_load_dwordx4 v[20:23], v178, s[4:5] offset:3072
	global_load_dwordx4 v[24:27], v178, s[6:7] offset:2048
	global_load_dwordx4 v[28:31], v178, s[6:7] offset:3072
	s_add_u32 s4, s2, 0x19100000
	v_lshlrev_b32_e32 v32, 1, v64
	s_addc_u32 s5, s3, 0
	v_lshlrev_b32_e32 v38, 1, v33
	v_ashrrev_i32_e32 v33, 31, v32
	v_or_b32_e32 v34, 1, v32
	v_lshlrev_b64 v[32:33], 11, v[32:33]
	s_add_u32 s6, s2, 0x13900000
	v_ashrrev_i32_e32 v65, 31, v64
	v_ashrrev_i32_e32 v35, 31, v34
	v_mov_b32_e32 v39, v179
	v_lshl_add_u64 v[32:33], s[4:5], 0, v[32:33]
	s_addc_u32 s7, s3, 0
	v_lshlrev_b64 v[44:45], 12, v[64:65]
	v_lshlrev_b64 v[34:35], 11, v[34:35]
	v_lshl_add_u64 v[42:43], v[32:33], 0, v[38:39]
	v_lshl_add_u64 v[32:33], s[6:7], 0, v[44:45]
	v_lshl_add_u64 v[34:35], s[4:5], 0, v[34:35]
	v_lshl_add_u64 v[46:47], v[32:33], 0, v[178:179]
	v_lshl_add_u64 v[40:41], v[34:35], 0, v[38:39]
	global_load_dwordx4 v[32:35], v[46:47], off offset:3072
	global_load_dwordx4 v[52:55], v[46:47], off offset:2048
	global_load_dwordx2 v[78:79], v[40:41], off offset:1536
	global_load_dwordx2 v[98:99], v[40:41], off offset:1024
	global_load_dwordx2 v[102:103], v[40:41], off offset:512
	global_load_dwordx2 v[106:107], v[40:41], off
	global_load_dwordx2 v[80:81], v[42:43], off offset:1536
	global_load_dwordx2 v[100:101], v[42:43], off offset:1024
	global_load_dwordx2 v[104:105], v[42:43], off offset:512
	global_load_dwordx2 v[108:109], v[42:43], off
	global_load_dwordx4 v[56:59], v[46:47], off offset:1024
	global_load_dwordx4 v[60:63], v[46:47], off
	v_and_b32_e32 v37, 64, v224
	v_lshl_add_u64 v[68:69], s[4:5], 0, v[38:39]
	v_add_u32_e32 v37, 64, v37
	v_xor_b32_e32 v38, 32, v224
	v_cmp_lt_i32_e32 vcc, v38, v37
	v_readlane_b32 s4, v254, 11
	v_readlane_b32 s5, v254, 12
	v_cndmask_b32_e32 v38, v224, v38, vcc
	s_waitcnt vmcnt(21)
	v_lshlrev_b32_e32 v120, 2, v38
	v_xor_b32_e32 v38, 16, v224
	v_cmp_lt_i32_e32 vcc, v38, v37
	v_lshl_add_u64 v[70:71], s[4:5], 0, v[178:179]
	v_readlane_b32 s4, v254, 13
	v_cndmask_b32_e32 v38, v224, v38, vcc
	v_lshlrev_b32_e32 v121, 2, v38
	v_xor_b32_e32 v38, 8, v224
	v_cmp_lt_i32_e32 vcc, v38, v37
	v_readlane_b32 s5, v254, 14
	v_lshl_add_u64 v[66:67], s[6:7], 0, v[178:179]
	v_cndmask_b32_e32 v38, v224, v38, vcc
	v_lshlrev_b32_e32 v122, 2, v38
	v_xor_b32_e32 v38, 4, v224
	v_cmp_lt_i32_e32 vcc, v38, v37
	v_lshl_add_u64 v[72:73], s[4:5], 0, v[178:179]
	v_and_b32_e32 v36, 63, v36
	v_cndmask_b32_e32 v38, v224, v38, vcc
	v_lshlrev_b32_e32 v123, 2, v38
	v_xor_b32_e32 v38, 2, v224
	v_cmp_lt_i32_e32 vcc, v38, v37
	v_readlane_b32 s4, v254, 45
	v_lshl_or_b32 v44, v36, 4, v44
	v_cndmask_b32_e32 v38, v224, v38, vcc
	s_waitcnt vmcnt(20)
	v_lshlrev_b32_e32 v124, 2, v38
	v_xor_b32_e32 v38, 1, v224
	v_cmp_lt_i32_e32 vcc, v38, v37
	v_readlane_b32 s5, v254, 46
	v_readlane_b32 s8, v254, 49
	v_cndmask_b32_e32 v37, v224, v38, vcc
	v_lshlrev_b32_e32 v125, 2, v37
	v_readlane_b32 s9, v254, 50
	v_lshl_add_u64 v[36:37], v[64:65], 3, s[2:3]
	s_mov_b64 s[2:3], 0x1d202100
	v_lshl_add_u64 v[74:75], s[8:9], 0, v[44:45]
	v_lshl_add_u64 v[76:77], v[36:37], 0, s[2:3]
	s_mov_b64 s[4:5], 0
	v_readlane_b32 s6, v254, 47
	v_readlane_b32 s7, v254, 48
	v_readlane_b32 s10, v254, 51
	v_readlane_b32 s11, v254, 52
	global_load_dwordx4 v[136:139], v[70:71], off offset:0
	global_load_dwordx4 v[152:155], v[72:73], off offset:0
	global_load_dwordx4 v[140:143], v[70:71], off offset:1024
	global_load_dwordx4 v[156:159], v[72:73], off offset:1024
	global_load_dwordx4 v[144:147], v[70:71], off offset:2048
	global_load_dwordx4 v[160:163], v[72:73], off offset:2048
	global_load_dwordx4 v[148:151], v[70:71], off offset:3072
	global_load_dwordx4 v[164:167], v[72:73], off offset:3072
	s_branch .Lfin_entry
.LBB0_987:
	s_waitcnt vmcnt(4)
	v_mov_b64_e32 v[104:105], v[84:85]
	v_mov_b64_e32 v[108:109], v[82:83]
	v_mov_b64_e32 v[102:103], v[90:91]
	v_mov_b64_e32 v[106:107], v[86:87]
	v_mov_b64_e32 v[80:81], v[94:95]
	v_mov_b64_e32 v[100:101], v[88:89]
	v_mov_b64_e32 v[78:79], v[96:97]
	v_mov_b64_e32 v[98:99], v[92:93]
	v_mov_b64_e32 v[34:35], v[50:51]
	v_mov_b64_e32 v[32:33], v[48:49]
	v_mov_b64_e32 v[54:55], v[46:47]
	v_mov_b64_e32 v[52:53], v[44:45]
	v_mov_b64_e32 v[58:59], v[42:43]
	v_mov_b64_e32 v[56:57], v[40:41]
	v_mov_b64_e32 v[62:63], v[38:39]
	v_mov_b64_e32 v[60:61], v[36:37]
.Lfin_entry:
	global_load_dwordx2 v[114:115], v[76:77], off
	v_add_u32_e32 v64, s50, v64
	v_min_i32_e32 v36, 0x3fff, v64
	v_ashrrev_i32_e32 v37, 31, v36
	v_lshlrev_b64 v[38:39], 12, v[36:37]
	v_lshlrev_b32_e32 v36, 1, v36
	v_ashrrev_i32_e32 v37, 31, v36
	v_lshl_add_u64 v[48:49], v[66:67], 0, v[38:39]
	v_lshlrev_b64 v[38:39], 11, v[36:37]
	v_or_b32_e32 v36, 1, v36
	v_ashrrev_i32_e32 v37, 31, v36
	v_lshlrev_b64 v[36:37], 11, v[36:37]
	v_lshl_add_u64 v[86:87], v[68:69], 0, v[38:39]
	v_lshl_add_u64 v[96:97], v[68:69], 0, v[36:37]
	global_load_dwordx4 v[36:39], v[48:49], off
	global_load_dwordx4 v[40:43], v[48:49], off offset:1024
	global_load_dwordx4 v[44:47], v[48:49], off offset:2048
	s_nop 0
	global_load_dwordx4 v[48:51], v[48:49], off offset:3072
	s_nop 0
	global_load_dwordx2 v[82:83], v[86:87], off
	global_load_dwordx2 v[84:85], v[86:87], off offset:512
	global_load_dwordx2 v[88:89], v[86:87], off offset:1024
	global_load_dwordx2 v[94:95], v[86:87], off offset:1536
	s_nop 0
	global_load_dwordx2 v[86:87], v[96:97], off
	global_load_dwordx2 v[90:91], v[96:97], off offset:512
	global_load_dwordx2 v[92:93], v[96:97], off offset:1024
	s_nop 0
	global_load_dwordx2 v[96:97], v[96:97], off offset:1536
	s_nop 0
	s_waitcnt vmcnt(12)
	v_mov_b64_e32 v[116:117], v[136:137]
	v_mov_b64_e32 v[118:119], v[138:139]
	v_mov_b64_e32 v[126:127], v[152:153]
	v_mov_b64_e32 v[128:129], v[154:155]
	v_lshlrev_b32_e32 v110, 16, v108
	v_and_b32_e32 v111, 0xffff0000, v108
	v_lshlrev_b32_e32 v112, 16, v106
	v_and_b32_e32 v113, 0xffff0000, v106
	v_lshlrev_b32_e32 v108, 16, v109
	v_and_b32_e32 v109, 0xffff0000, v109
	v_lshlrev_b32_e32 v106, 16, v107
	v_and_b32_e32 v107, 0xffff0000, v107
	v_pk_add_f32 v[106:107], v[108:109], v[106:107]
	v_lshlrev_b32_e32 v108, 16, v104
	v_and_b32_e32 v109, 0xffff0000, v104
	v_lshlrev_b32_e32 v104, 16, v105
	v_and_b32_e32 v105, 0xffff0000, v105
	v_pk_add_f32 v[110:111], v[110:111], v[112:113]
	v_lshl_add_u64 v[76:77], v[76:77], 0, s[62:63]
	v_pk_add_f32 v[60:61], v[60:61], v[114:115] op_sel_hi:[1,0] neg_lo:[0,1] neg_hi:[0,1]
	v_pk_add_f32 v[62:63], v[62:63], v[114:115] op_sel_hi:[1,0] neg_lo:[0,1] neg_hi:[0,1]
	v_pk_mul_f32 v[60:61], v[114:115], v[60:61] op_sel:[1,0]
	v_pk_mul_f32 v[62:63], v[114:115], v[62:63] op_sel:[1,0]
	v_pk_fma_f32 v[60:61], v[116:117], v[60:61], v[126:127]
	v_pk_fma_f32 v[62:63], v[118:119], v[62:63], v[128:129]
	v_mov_b64_e32 v[116:117], v[140:141]
	v_mov_b64_e32 v[118:119], v[142:143]
	v_mov_b64_e32 v[126:127], v[156:157]
	v_mov_b64_e32 v[128:129], v[158:159]
	v_pk_add_f32 v[56:57], v[56:57], v[114:115] op_sel_hi:[1,0] neg_lo:[0,1] neg_hi:[0,1]
	v_pk_add_f32 v[58:59], v[58:59], v[114:115] op_sel_hi:[1,0] neg_lo:[0,1] neg_hi:[0,1]
	v_pk_mul_f32 v[56:57], v[114:115], v[56:57] op_sel:[1,0]
	v_pk_mul_f32 v[58:59], v[114:115], v[58:59] op_sel:[1,0]
	v_pk_add_f32 v[52:53], v[52:53], v[114:115] op_sel_hi:[1,0] neg_lo:[0,1] neg_hi:[0,1]
	v_pk_add_f32 v[54:55], v[54:55], v[114:115] op_sel_hi:[1,0] neg_lo:[0,1] neg_hi:[0,1]
	v_pk_mul_f32 v[52:53], v[114:115], v[52:53] op_sel:[1,0]
	v_pk_mul_f32 v[54:55], v[114:115], v[54:55] op_sel:[1,0]
	v_pk_add_f32 v[32:33], v[32:33], v[114:115] op_sel_hi:[1,0] neg_lo:[0,1] neg_hi:[0,1]
	v_pk_fma_f32 v[60:61], v[60:61], s[84:85], v[110:111] op_sel_hi:[1,0,1]
	v_pk_mul_f32 v[32:33], v[114:115], v[32:33] op_sel:[1,0]
	v_pk_add_f32 v[110:111], v[60:61], v[60:61] op_sel:[0,1] op_sel_hi:[1,0]
	v_pk_mul_f32 v[112:113], v[60:61], v[60:61]
	v_pk_fma_f32 v[62:63], v[62:63], s[84:85], v[106:107] op_sel_hi:[1,0,1]
	v_pk_add_f32 v[34:35], v[34:35], v[114:115] op_sel_hi:[1,0] neg_lo:[0,1] neg_hi:[0,1]
	v_pk_mul_f32 v[106:107], v[62:63], v[62:63]
	v_pk_mul_f32 v[34:35], v[114:115], v[34:35] op_sel:[1,0]
	v_mov_b32_e32 v178, v107
	v_pk_fma_f32 v[56:57], v[116:117], v[56:57], v[126:127]
	v_pk_fma_f32 v[58:59], v[118:119], v[58:59], v[128:129]
	v_mov_b64_e32 v[126:127], v[144:145]
	v_mov_b64_e32 v[128:129], v[146:147]
	v_mov_b64_e32 v[130:131], v[160:161]
	v_mov_b64_e32 v[132:133], v[162:163]
	v_lshlrev_b32_e32 v116, 16, v102
	v_and_b32_e32 v117, 0xffff0000, v102
	v_pk_add_f32 v[108:109], v[108:109], v[116:117]
	v_lshlrev_b32_e32 v118, 16, v98
	v_pk_fma_f32 v[56:57], v[56:57], s[84:85], v[108:109] op_sel_hi:[1,0,1]
	v_and_b32_e32 v119, 0xffff0000, v98
	v_mul_f32_e32 v102, v57, v57
	v_pk_fma_f32 v[116:117], v[56:57], v[56:57], v[102:103] op_sel_hi:[1,1,0]
	v_lshlrev_b32_e32 v102, 16, v103
	v_and_b32_e32 v103, 0xffff0000, v103
	v_pk_add_f32 v[102:103], v[104:105], v[102:103]
	v_lshlrev_b32_e32 v104, 16, v100
	v_and_b32_e32 v105, 0xffff0000, v100
	v_pk_add_f32 v[104:105], v[104:105], v[118:119]
	v_lshlrev_b32_e32 v100, 16, v101
	v_and_b32_e32 v101, 0xffff0000, v101
	v_pk_fma_f32 v[58:59], v[58:59], s[84:85], v[102:103] op_sel_hi:[1,0,1]
	v_pk_add_f32 v[108:109], v[56:57], v[56:57] op_sel_hi:[0,1]
	v_pk_mul_f32 v[102:103], v[58:59], v[58:59]
	v_mov_b32_e32 v117, v58
	v_mov_b32_e32 v108, v102
	v_mov_b32_e32 v102, v103
	v_mov_b32_e32 v103, v59
	v_pk_fma_f32 v[52:53], v[126:127], v[52:53], v[130:131]
	v_pk_fma_f32 v[54:55], v[128:129], v[54:55], v[132:133]
	v_mov_b64_e32 v[126:127], v[148:149]
	v_mov_b64_e32 v[128:129], v[150:151]
	v_mov_b64_e32 v[130:131], v[164:165]
	v_mov_b64_e32 v[132:133], v[166:167]
	v_pk_fma_f32 v[52:53], v[52:53], s[84:85], v[104:105] op_sel_hi:[1,0,1]
	v_pk_fma_f32 v[32:33], v[126:127], v[32:33], v[130:131]
	v_mul_f32_e32 v98, v53, v53
	v_pk_fma_f32 v[118:119], v[52:53], v[52:53], v[98:99] op_sel_hi:[1,1,0]
	v_lshlrev_b32_e32 v98, 16, v99
	v_and_b32_e32 v99, 0xffff0000, v99
	v_pk_add_f32 v[98:99], v[100:101], v[98:99]
	v_lshlrev_b32_e32 v100, 16, v80
	v_and_b32_e32 v101, 0xffff0000, v80
	v_lshlrev_b32_e32 v126, 16, v78
	v_and_b32_e32 v127, 0xffff0000, v78
	v_pk_add_f32 v[100:101], v[100:101], v[126:127]
	v_lshlrev_b32_e32 v80, 16, v81
	v_and_b32_e32 v81, 0xffff0000, v81
	v_lshlrev_b32_e32 v78, 16, v79
	v_and_b32_e32 v79, 0xffff0000, v79
	v_pk_fma_f32 v[100:101], v[32:33], s[84:85], v[100:101] op_sel_hi:[1,0,1]
	v_pk_add_f32 v[78:79], v[80:81], v[78:79]
	v_mov_b32_e32 v80, v112
	v_mov_b32_e32 v81, v110
	v_pk_mov_b32 v[110:111], v[112:113], v[62:63] op_sel:[1,0]
	v_pk_fma_f32 v[54:55], v[54:55], s[84:85], v[98:99] op_sel_hi:[1,0,1]
	v_pk_add_f32 v[32:33], v[100:101], v[100:101] op_sel_hi:[0,1]
	v_pk_fma_f32 v[34:35], v[128:129], v[34:35], v[132:133]
	v_pk_add_f32 v[80:81], v[80:81], v[110:111]
	v_mov_b32_e32 v110, v106
	v_mov_b32_e32 v111, v63
	v_pk_add_f32 v[104:105], v[52:53], v[52:53] op_sel_hi:[0,1]
	v_pk_mul_f32 v[98:99], v[54:55], v[54:55]
	v_mul_f32_e32 v32, v101, v101
	v_pk_fma_f32 v[78:79], v[34:35], s[84:85], v[78:79] op_sel_hi:[1,0,1]
	v_pk_add_f32 v[80:81], v[80:81], v[110:111]
	v_pk_add_f32 v[106:107], v[108:109], v[116:117]
	v_pk_fma_f32 v[126:127], v[100:101], v[100:101], v[32:33] op_sel_hi:[1,1,0]
	v_pk_mul_f32 v[34:35], v[78:79], v[78:79]
	v_pk_add_f32 v[80:81], v[80:81], v[178:179]
	v_pk_add_f32 v[102:103], v[106:107], v[102:103]
	v_mov_b32_e32 v104, v98
	v_mov_b32_e32 v119, v54
	v_pk_add_f32 v[80:81], v[80:81], v[102:103]
	v_pk_add_f32 v[102:103], v[104:105], v[118:119]
	v_mov_b32_e32 v98, v99
	v_mov_b32_e32 v99, v55
	v_mov_b32_e32 v32, v34
	v_mov_b32_e32 v127, v78
	v_pk_add_f32 v[98:99], v[102:103], v[98:99]
	v_pk_add_f32 v[32:33], v[32:33], v[126:127]
	v_mov_b32_e32 v34, v35
	v_mov_b32_e32 v35, v79
	v_pk_add_f32 v[80:81], v[80:81], v[98:99]
	v_pk_add_f32 v[32:33], v[32:33], v[34:35]
	v_pk_add_f32 v[32:33], v[80:81], v[32:33]
	ds_bpermute_b32 v35, v120, v33
	ds_bpermute_b32 v34, v120, v32
	s_waitcnt lgkmcnt(0)
	v_pk_add_f32 v[32:33], v[32:33], v[34:35]
	ds_bpermute_b32 v35, v121, v33
	ds_bpermute_b32 v34, v121, v32
	s_waitcnt lgkmcnt(0)
	v_pk_add_f32 v[32:33], v[32:33], v[34:35]
	ds_bpermute_b32 v35, v122, v33
	ds_bpermute_b32 v34, v122, v32
	s_waitcnt lgkmcnt(0)
	v_pk_add_f32 v[32:33], v[32:33], v[34:35]
	ds_bpermute_b32 v35, v123, v33
	ds_bpermute_b32 v34, v123, v32
	s_waitcnt lgkmcnt(0)
	v_pk_add_f32 v[32:33], v[32:33], v[34:35]
	ds_bpermute_b32 v35, v124, v33
	ds_bpermute_b32 v34, v124, v32
	s_waitcnt lgkmcnt(0)
	v_pk_add_f32 v[32:33], v[32:33], v[34:35]
	ds_bpermute_b32 v35, v125, v33
	ds_bpermute_b32 v34, v125, v32
	s_waitcnt lgkmcnt(0)
	v_pk_add_f32 v[32:33], v[32:33], v[34:35]
	s_nop 0
	v_pk_mul_f32 v[80:81], v[32:33], s[16:17] op_sel_hi:[1,0]
	s_nop 0
	v_fma_f32 v32, -v81, v81, v80
	v_max_f32_e32 v32, 0, v32
	v_add_f32_e32 v32, 0x3727c5ac, v32
	v_cmp_gt_f32_e32 vcc, s70, v32
	v_mul_f32_e32 v33, 0x4b800000, v32
	v_pk_add_f32 v[34:35], v[62:63], v[80:81] op_sel:[0,1] neg_lo:[0,1] neg_hi:[0,1]
	v_cndmask_b32_e32 v32, v32, v33, vcc
	v_rsq_f32_e32 v32, v32
	v_pk_add_f32 v[56:57], v[56:57], v[80:81] op_sel:[0,1] neg_lo:[0,1] neg_hi:[0,1]
	v_pk_add_f32 v[58:59], v[58:59], v[80:81] op_sel:[0,1] neg_lo:[0,1] neg_hi:[0,1]
	v_pk_add_f32 v[52:53], v[52:53], v[80:81] op_sel:[0,1] neg_lo:[0,1] neg_hi:[0,1]
	v_mul_f32_e32 v33, 0x45800000, v32
	v_cndmask_b32_e32 v98, v32, v33, vcc
	v_pk_add_f32 v[32:33], v[60:61], v[80:81] op_sel:[0,1] neg_lo:[0,1] neg_hi:[0,1]
	v_pk_add_f32 v[54:55], v[54:55], v[80:81] op_sel:[0,1] neg_lo:[0,1] neg_hi:[0,1]
	v_pk_add_f32 v[60:61], v[100:101], v[80:81] op_sel:[0,1] neg_lo:[0,1] neg_hi:[0,1]
	v_pk_add_f32 v[62:63], v[78:79], v[80:81] op_sel:[0,1] neg_lo:[0,1] neg_hi:[0,1]
	v_pk_mul_f32 v[32:33], v[32:33], v[98:99] op_sel_hi:[1,0]
	v_pk_mul_f32 v[34:35], v[34:35], v[98:99] op_sel_hi:[1,0]
	v_pk_mul_f32 v[56:57], v[56:57], v[98:99] op_sel_hi:[1,0]
	v_pk_mul_f32 v[58:59], v[58:59], v[98:99] op_sel_hi:[1,0]
	v_pk_mul_f32 v[52:53], v[52:53], v[98:99] op_sel_hi:[1,0]
	v_pk_mul_f32 v[54:55], v[54:55], v[98:99] op_sel_hi:[1,0]
	v_pk_mul_f32 v[60:61], v[60:61], v[98:99] op_sel_hi:[1,0]
	v_pk_mul_f32 v[62:63], v[62:63], v[98:99] op_sel_hi:[1,0]
	v_pk_fma_f32 v[32:33], v[0:1], v[32:33], v[8:9]
	v_pk_fma_f32 v[34:35], v[2:3], v[34:35], v[10:11]
	v_pk_fma_f32 v[56:57], v[56:57], v[4:5], v[12:13]
	v_pk_fma_f32 v[58:59], v[58:59], v[6:7], v[14:15]
	v_pk_fma_f32 v[52:53], v[52:53], v[16:17], v[24:25]
	v_pk_fma_f32 v[54:55], v[54:55], v[18:19], v[26:27]
	v_pk_fma_f32 v[60:61], v[60:61], v[20:21], v[28:29]
	v_pk_fma_f32 v[62:63], v[62:63], v[22:23], v[30:31]
	v_cmp_lt_i32_e32 vcc, s44, v64
	global_store_dwordx4 v[74:75], v[32:35], off
	global_store_dwordx4 v[74:75], v[56:59], off offset:1024
	global_store_dwordx4 v[74:75], v[52:55], off offset:2048
	global_store_dwordx4 v[74:75], v[60:63], off offset:3072
	v_lshl_add_u64 v[74:75], v[74:75], 0, s[14:15]
	s_or_b64 s[4:5], vcc, s[4:5]
	s_andn2_b64 exec, exec, s[4:5]
	s_cbranch_execnz .LBB0_987
